# phase-8 segment priorities: pre-step (far-memory bound) s_setprio 3, u-side 0, v-side 2
# baseline (speedup 1.0000x reference)
; __device__ void phase_gather_u(const Params& p) {
;   const int tid = threadIdx.x, lane = tid & 63, wid = tid >> 6;
;   unsigned char* ws = p.ws;
;   const unsigned char* ub = ws + OFF_XB;
;   const int* idxg = (const int*)(ws + OFF_IDX);
;   u32x4* xq = (u32x4*)(ws + OFF_XQ);
;   int* wbuf = (int*)(ws + OFF_WBUF);
;   float* sxa = (float*)(ws + OFF_WBUF + 8 * MIB);
;   const bool b5 = (lane & 32) != 0, b4 = (lane & 16) != 0, b3 = (lane & 8) != 0;
;   const int srcl = ((lane & 1) << 3) | (((lane >> 1) & 1) << 4) | (((lane >> 2) & 1) << 5);
;   const int tbase = blockIdx.x * 8 + wid, tstride = gridDim.x * 8;
;   for (int t = tbase; t < T_TOK; t += tstride) {
;     const float* orow = p.out + (size_t)t * DM + lane * 32;
;     float xr[32];
;     float amax = 0.f;
; #pragma unroll
;     for (int q = 0; q < 8; ++q) {
;       f32x4 v = *(const f32x4*)(orow + q * 4);
; #pragma unroll
;       for (int k = 0; k < 4; ++k) { xr[q * 4 + k] = v[k]; amax = fmaxf(amax, fabsf(v[k])); }
;     }
; #pragma unroll
;     for (int o = 32; o > 0; o >>= 1) amax = fmaxf(amax, __shfl_xor(amax, o));
.LBB0_1199:
	s_cmp_lt_i32 s56, 9
	s_cselect_b64 s[4:5], -1, 0
	s_and_b64 s[0:1], s[4:5], s[0:1]
	s_andn2_b64 vcc, exec, s[0:1]
	s_cbranch_vccnz .LBB0_1323
	s_setprio 3
	v_lshl_add_u32 v112, s2, 3, v164
	s_movk_i32 s0, 0x4000
	s_lshl_b32 s68, s96, 3
	v_cmp_gt_i32_e64 s[0:1], s0, v112
	v_mbcnt_lo_u32_b32 v30, -1, 0
	s_and_saveexec_b64 s[4:5], s[0:1]
	s_cbranch_execz .LBB0_1205
	v_mbcnt_hi_u32_b32 v0, -1, v30
	v_and_b32_e32 v1, 64, v0
	v_add_u32_e32 v1, 64, v1
	v_xor_b32_e32 v2, 32, v0
	v_cmp_lt_i32_e32 vcc, v2, v1
	v_ashrrev_i32_e32 v113, 31, v112
	s_mov_b64 s[6:7], 0x17c00000
	v_cndmask_b32_e32 v2, v0, v2, vcc
	v_lshlrev_b32_e32 v31, 2, v2
	v_xor_b32_e32 v2, 16, v0
	v_cmp_lt_i32_e32 vcc, v2, v1
	s_mov_b64 s[8:9], 0x15400000
	s_ashr_i32 s69, s68, 31
	v_cndmask_b32_e32 v2, v0, v2, vcc
	v_lshlrev_b32_e32 v32, 2, v2
	v_xor_b32_e32 v2, 8, v0
	v_cmp_lt_i32_e32 vcc, v2, v1
	v_cmp_eq_u32_e64 s[2:3], 0, v138
	s_lshl_b64 s[10:11], s[68:69], 13
	v_cndmask_b32_e32 v2, v0, v2, vcc
	v_lshlrev_b32_e32 v33, 2, v2
	v_xor_b32_e32 v2, 4, v0
	v_cmp_lt_i32_e32 vcc, v2, v1
	s_mov_b64 s[12:13], 0
	s_mov_b32 s16, 0x42ee0000
	v_cndmask_b32_e32 v2, v0, v2, vcc
	v_lshlrev_b32_e32 v34, 2, v2
	v_xor_b32_e32 v2, 2, v0
	v_cmp_lt_i32_e32 vcc, v2, v1
	s_movk_i32 s17, 0xf0
	s_movk_i32 s18, 0x3fff
	v_cndmask_b32_e32 v2, v0, v2, vcc
	v_lshlrev_b32_e32 v35, 2, v2
	v_xor_b32_e32 v2, 1, v0
	v_cmp_lt_i32_e32 vcc, v2, v1
	v_mov_b32_e32 v37, 15
	v_mov_b32_e32 v38, v112
	v_cndmask_b32_e32 v0, v0, v2, vcc
	v_lshlrev_b32_e32 v36, 2, v0
	v_lshl_add_u64 v[0:1], v[112:113], 2, s[34:35]
	v_lshl_add_u64 v[24:25], v[0:1], 0, s[6:7]
	v_lshlrev_b64 v[0:1], 11, v[112:113]
	v_lshl_or_b32 v0, v138, 5, v0
	v_lshl_add_u64 v[0:1], s[34:35], 0, v[0:1]
	v_lshl_add_u64 v[26:27], v[0:1], 0, s[8:9]
	v_lshlrev_b64 v[0:1], 13, v[112:113]
	v_lshl_or_b32 v0, v138, 7, v0
	s_lshl_b64 s[6:7], s[68:69], 2
	s_lshl_b64 s[8:9], s[68:69], 11
	v_lshl_add_u64 v[28:29], s[30:31], 0, v[0:1]
	v_lshrrev_b32_e32 v64, 6, v139
	v_lshlrev_b32_e32 v64, 14, v64
	v_lshl_add_u32 v64, v138, 5, v64
	v_add_u32_e32 v64, 0x2000, v64
	s_branch .LBB0_1203

; __device__ void phase_gather_u(const Params& p) {
;     ...
; #pragma unroll 1
;   for (int r = 0; r < 4; ++r) {
; #pragma unroll 1
;     for (int t = tbase; t < T_TOK; t += tstride) {
;       const u32x4 ph = xq[((size_t)t * 64 + lane) * 2], pl = xq[((size_t)t * 64 + lane) * 2 + 1];
;       const int idA = idxg[(size_t)t * 128 + lane], idB = idxg[(size_t)t * 128 + 64 + lane];
;       unsigned long long m0 = __ballot((idA >> 12) == r), m1 = __ballot((idB >> 12) == r);
.LBB0_1205:
	s_setprio 0
	s_or_b64 exec, exec, s[4:5]
	v_and_b32_e32 v0, 32, v139
	v_cmp_eq_u32_e64 s[2:3], 0, v0
	v_and_b32_e32 v0, 16, v139
	v_cmp_eq_u32_e64 s[4:5], 0, v0
	v_and_b32_e32 v0, 8, v139
	s_add_u32 s10, s34, 0xc000000
	v_cmp_eq_u32_e64 s[6:7], 0, v0
	v_mov_b32_e32 v1, 0
	v_lshlrev_b32_e32 v0, 5, v138
	s_addc_u32 s11, s35, 0
	s_waitcnt lgkmcnt(0)
	v_lshl_add_u64 v[2:3], s[34:35], 0, v[0:1]
	v_lshlrev_b32_e32 v0, 2, v138
	v_lshlrev_b32_e32 v82, 3, v139
	v_writelane_b32 v250, s10, 18
	v_mbcnt_hi_u32_b32 v83, -1, v30
	v_and_b32_e32 v4, 56, v82
	v_lshl_add_u64 v[76:77], s[10:11], 0, v[0:1]
	v_lshlrev_b32_e32 v0, 4, v138
	s_waitcnt vmcnt(0)
	v_lshl_add_u64 v[72:73], s[34:35], 0, v[0:1]
	v_and_b32_e32 v0, 64, v83
	s_add_u32 s70, s34, 0x17400000
	s_mov_b64 s[8:9], 0x15400000
	v_add_u32_e32 v84, 64, v0
	v_or_b32_e32 v0, v0, v4
	s_addc_u32 s71, s35, 0
	s_mov_b32 s33, 0
	v_lshl_add_u64 v[74:75], v[2:3], 0, s[8:9]
	v_writelane_b32 v250, s11, 19
	v_cmp_gt_u32_e64 s[8:9], 8, v138
	v_cmp_eq_u32_e64 s[10:11], 1, v138
	v_cmp_eq_u32_e64 s[12:13], 2, v138
	v_cmp_eq_u32_e64 s[14:15], 3, v138
	v_cmp_eq_u32_e64 s[16:17], 4, v138
	v_cmp_eq_u32_e64 s[18:19], 5, v138
	v_cmp_eq_u32_e64 s[20:21], 6, v138
	v_cmp_eq_u32_e64 s[22:23], 7, v138
	s_movk_i32 s48, 0x3fff
	v_xor_b32_e32 v89, 32, v83
	v_xor_b32_e32 v90, 16, v83
	v_xor_b32_e32 v88, 8, v83
	v_xor_b32_e32 v87, 4, v83
	v_xor_b32_e32 v86, 2, v83
	v_xor_b32_e32 v85, 1, v83
	v_lshlrev_b32_e32 v91, 2, v0
	v_and_b32_e32 v96, 15, v138
	v_lshrrev_b32_e32 v99, 4, v138
	v_lshlrev_b32_e32 v98, 2, v138
	v_lshrrev_b32_e32 v100, 6, v139
	v_cmp_eq_u32_e64 s[8:9], 0, v96
	v_lshlrev_b32_e32 v97, 5, v96
	v_lshlrev_b32_e32 v96, 4, v96
	v_readfirstlane_b32 s60, v100
	v_readfirstlane_b32 s61, v112
	s_add_u32 s64, s34, 0x15400000
	s_addc_u32 s65, s35, 0
	s_add_u32 s62, s34, 0xc000000
	s_addc_u32 s63, s35, 0
	s_lshl_b32 s60, s60, 10
	s_and_saveexec_b64 s[38:39], s[0:1]
	s_cbranch_execz .Lgu_done
	s_mov_b32 s33, 0
	s_mov_b32 s66, 0
	s_lshl_b32 s72, s60, 4
	s_add_i32 s72, s72, 0x2000
	s_lshl_b32 s40, s61, 9
	s_add_u32 s40, s62, s40
	s_addc_u32 s41, s63, 0
	global_load_dword v94, v98, s[40:41]
	global_load_dword v95, v98, s[40:41] offset:256
	s_add_i32 s37, s61, s68
	s_lshl_b32 s40, s37, 9
	s_add_u32 s40, s62, s40
	s_addc_u32 s41, s63, 0
	global_load_dword v232, v98, s[40:41]
	global_load_dword v233, v98, s[40:41] offset:256
	s_waitcnt vmcnt(2)
	s_mov_b32 s67, 0xfffffc00
